# P2 int8-r epilogue: the three later row-scale loads issued together with the first one (free registers, readers renamed) instead of one exposed round trip per round
# baseline (speedup 1.0000x reference)
.LBB0_375:
	v_lshl_add_u32 v204, s54, 8, v227
	v_ashrrev_i32_e32 v205, 31, v204
	v_lshl_add_u64 v[4:5], v[204:205], 2, s[24:25]
	global_load_dwordx4 v[0:3], v[4:5], off offset:16
	s_nop 0
	global_load_dwordx4 v[4:7], v[4:5], off
	s_lshl_b32 s8, s55, 8
	v_or_b32_e32 v8, s8, v228
	v_ashrrev_i32_e32 v9, 31, v8
	v_lshl_add_u64 v[150:151], v[8:9], 2, s[26:27]
	global_load_dwordx4 v[8:11], v[150:151], off
	global_load_dwordx4 v[240:243], v[150:151], off offset:64
	global_load_dwordx4 v[244:247], v[150:151], off offset:512
	global_load_dwordx4 v[248:251], v[150:151], off offset:576
	s_waitcnt vmcnt(0)
	v_mov_b32_e32 v24, v3
	v_mov_b32_e32 v106, v2
	v_mov_b32_e32 v107, v2
	v_mov_b32_e32 v110, v2
	v_mov_b32_e32 v111, v2
	v_mov_b32_e32 v118, v3
	v_mov_b32_e32 v119, v3
	v_mov_b32_e32 v122, v3
	v_mov_b32_e32 v123, v3
	v_mov_b32_e32 v20, 0
	v_mov_b32_e32 v21, 0
	v_mov_b32_e32 v22, 0
	v_mov_b32_e32 v23, 0
	v_mov_b32_e32 v16, 0
	v_mov_b32_e32 v17, 0
	v_mov_b32_e32 v18, 0
	v_mov_b32_e32 v19, 0
	v_mov_b32_e32 v12, 0
	v_mov_b32_e32 v13, 0
	v_mov_b32_e32 v14, 0
	v_mov_b32_e32 v15, 0
	v_mov_b32_e32 v102, v1
	v_mov_b32_e32 v103, v1
	v_mov_b32_e32 v104, v1
	v_mov_b32_e32 v105, v1
	v_cmp_gt_i32_e32 vcc, 15, v223
	v_pk_mul_f32 v[28:29], v[8:9], v[152:153]
	v_or_b32_e32 v152, s8, v225
	v_ashrrev_i32_e32 v153, 31, v152
	v_pk_mul_f32 v[30:31], v[10:11], v[168:169]
	v_pk_mul_f32 v[32:33], v[8:9], v[156:157]
	v_pk_mul_f32 v[34:35], v[10:11], v[208:209]
	v_pk_mul_f32 v[36:37], v[8:9], v[206:207]
	v_lshlrev_b64 v[40:41], 2, v[152:153]
	v_pk_mul_f32 v[26:27], v[10:11], v[154:155]
	v_pk_mul_f32 v[46:47], v[2:3], v[30:31] op_sel_hi:[0,1]
	v_pk_mul_f32 v[208:209], v[2:3], v[32:33] op_sel_hi:[0,1]
	v_pk_mul_f32 v[44:45], v[24:25], v[34:35] op_sel_hi:[0,1]
	v_pk_mul_f32 v[2:3], v[24:25], v[36:37] op_sel_hi:[0,1]
	v_lshl_add_u64 v[154:155], s[10:11], 0, v[40:41]
	v_lshl_add_u64 v[24:25], s[40:41], 0, v[40:41]
	v_pk_mul_f32 v[206:207], v[0:1], v[26:27] op_sel:[1,0]
	v_pk_mul_f32 v[48:49], v[0:1], v[28:29] op_sel:[1,0]
	global_load_dwordx4 v[28:31], v[154:155], off
	v_lshl_add_u64 v[26:27], s[42:43], 0, v[40:41]
	global_load_dwordx4 v[36:39], v[24:25], off
	global_load_dwordx4 v[32:35], v[26:27], off
	v_lshl_add_u64 v[24:25], s[44:45], 0, v[40:41]
	v_lshl_add_u64 v[156:157], s[12:13], 0, v[40:41]
	global_load_dwordx4 v[24:27], v[24:25], off
	v_mov_b32_dpp v20, v48 row_shr:1 row_mask:0xf bank_mask:0xf
	global_load_dwordx4 v[40:43], v[156:157], off
	v_mov_b32_dpp v21, v49 row_shr:1 row_mask:0xf bank_mask:0xf
	v_mov_b32_dpp v22, v206 row_shr:1 row_mask:0xf bank_mask:0xf
	v_mov_b32_dpp v23, v207 row_shr:1 row_mask:0xf bank_mask:0xf
	v_mov_b32_dpp v16, v208 row_shr:1 row_mask:0xf bank_mask:0xf
	v_mov_b32_dpp v17, v209 row_shr:1 row_mask:0xf bank_mask:0xf
	v_mov_b32_dpp v18, v46 row_shr:1 row_mask:0xf bank_mask:0xf
	v_mov_b32_dpp v19, v47 row_shr:1 row_mask:0xf bank_mask:0xf
	v_mov_b32_dpp v12, v2 row_shr:1 row_mask:0xf bank_mask:0xf
	v_mov_b32_dpp v13, v3 row_shr:1 row_mask:0xf bank_mask:0xf
	v_mov_b32_dpp v14, v44 row_shr:1 row_mask:0xf bank_mask:0xf
	v_mov_b32_dpp v15, v45 row_shr:1 row_mask:0xf bank_mask:0xf
	s_mov_b64 s[8:9], -1
	s_and_saveexec_b64 s[56:57], vcc
	v_cmp_eq_u32_e32 vcc, 0, v223
	s_orn2_b64 s[8:9], vcc, exec
	s_or_b64 exec, exec, s[56:57]
	s_lshl_b32 s20, s54, 1
	v_pk_mul_f32 v[124:125], v[8:9], v[124:125]
	s_add_i32 s20, s20, s18
	v_pk_mul_f32 v[220:221], v[4:5], v[124:125] op_sel_hi:[0,1]
	v_pk_mul_f32 v[124:125], v[10:11], v[164:165]
	s_mul_i32 s20, s20, 6
	v_pk_mul_f32 v[146:147], v[10:11], v[146:147]
	v_pk_mul_f32 v[120:121], v[8:9], v[120:121]
	v_pk_mul_f32 v[214:215], v[4:5], v[124:125] op_sel:[1,0]
	v_pk_mul_f32 v[124:125], v[8:9], v[148:149]
	v_pk_mul_f32 v[218:219], v[4:5], v[146:147] op_sel_hi:[0,1]
	v_pk_mul_f32 v[216:217], v[4:5], v[120:121] op_sel:[1,0]
	v_pk_mul_f32 v[120:121], v[10:11], v[166:167]
	v_pk_mul_f32 v[210:211], v[6:7], v[124:125] op_sel_hi:[0,1]
	v_add_u32_e32 v148, s20, v229
	v_add_u32_e32 v146, s20, v230
	v_add_u32_e32 v124, s20, v231
	v_pk_mul_f32 v[212:213], v[6:7], v[120:121] op_sel_hi:[0,1]
	v_lshlrev_b64 v[120:121], 1, v[152:153]
	v_ashrrev_i32_e32 v149, 31, v148
	v_ashrrev_i32_e32 v147, 31, v146
	v_ashrrev_i32_e32 v125, 31, v124
	s_and_saveexec_b64 s[54:55], s[8:9]
	s_cbranch_execz .LBB0_379
	v_lshlrev_b64 v[166:167], 11, v[148:149]
	v_lshl_add_u64 v[166:167], s[30:31], 0, v[166:167]
	v_cndmask_b32_e64 v164, v48, v220, s[4:5]
	v_cndmask_b32_e64 v165, v49, v221, s[4:5]
	v_lshl_add_u64 v[166:167], v[166:167], 0, v[120:121]
	v_cndmask_b32_e64 v1, v206, v218, s[4:5]
	v_cndmask_b32_e64 v153, v207, v219, s[4:5]
	v_cvt_pk_bf16_f32 v164, v164, v165
	v_cvt_pk_bf16_f32 v165, v1, v153
	global_store_dwordx2 v[166:167], v[164:165], off
	v_lshlrev_b64 v[166:167], 11, v[146:147]
	v_lshl_add_u64 v[166:167], s[30:31], 0, v[166:167]
	v_cndmask_b32_e64 v164, v208, v216, s[4:5]
	v_cndmask_b32_e64 v165, v209, v217, s[4:5]
	v_lshl_add_u64 v[166:167], v[166:167], 0, v[120:121]
	v_cndmask_b32_e64 v1, v46, v214, s[4:5]
	v_cndmask_b32_e64 v153, v47, v215, s[4:5]
	v_cvt_pk_bf16_f32 v164, v164, v165
	v_cvt_pk_bf16_f32 v165, v1, v153
	global_store_dwordx2 v[166:167], v[164:165], off
	v_lshlrev_b64 v[166:167], 11, v[124:125]
	v_lshl_add_u64 v[166:167], s[30:31], 0, v[166:167]
	v_cndmask_b32_e64 v164, v2, v210, s[4:5]
	v_cndmask_b32_e64 v165, v3, v211, s[4:5]
	v_lshl_add_u64 v[166:167], v[166:167], 0, v[120:121]
	v_cndmask_b32_e64 v1, v44, v212, s[4:5]
	v_cndmask_b32_e64 v153, v45, v213, s[4:5]
	v_cvt_pk_bf16_f32 v164, v164, v165
	v_cvt_pk_bf16_f32 v165, v1, v153
	global_store_dwordx2 v[166:167], v[164:165], off
.LBB0_379:
	s_or_b64 exec, exec, s[54:55]
	v_pk_mul_f32 v[234:235], v[10:11], v[160:161]
	v_pk_mul_f32 v[10:11], v[10:11], v[202:203]
	v_mov_b32_e32 v1, v0
	v_pk_mul_f32 v[202:203], v[0:1], v[10:11] op_sel_hi:[0,1]
	s_waitcnt vmcnt(0)
	v_pk_fma_f32 v[10:11], v[30:31], v[22:23], v[42:43]
	v_pk_fma_f32 v[20:21], v[28:29], v[20:21], v[40:41]
	v_pk_fma_f32 v[10:11], v[38:39], v[18:19], v[10:11]
	v_pk_fma_f32 v[20:21], v[36:37], v[16:17], v[20:21]
	v_pk_fma_f32 v[10:11], v[34:35], v[14:15], v[10:11]
	v_pk_fma_f32 v[20:21], v[32:33], v[12:13], v[20:21]
	v_pk_fma_f32 v[10:11], v[218:219], v[26:27], v[10:11]
	v_pk_fma_f32 v[20:21], v[220:221], v[24:25], v[20:21]
	v_pk_fma_f32 v[16:17], v[28:29], v[16:17], v[40:41]
	v_cvt_pk_bf16_f32 v22, v20, v21
	v_cvt_pk_bf16_f32 v23, v10, v11
	v_pk_fma_f32 v[10:11], v[30:31], v[18:19], v[42:43]
	v_pk_fma_f32 v[16:17], v[36:37], v[12:13], v[16:17]
	v_pk_fma_f32 v[10:11], v[38:39], v[14:15], v[10:11]
	v_pk_fma_f32 v[16:17], v[220:221], v[32:33], v[16:17]
	v_pk_fma_f32 v[10:11], v[218:219], v[34:35], v[10:11]
	v_pk_fma_f32 v[16:17], v[216:217], v[24:25], v[16:17]
	v_pk_fma_f32 v[10:11], v[214:215], v[26:27], v[10:11]
	v_cvt_pk_bf16_f32 v20, v16, v17
	v_pk_fma_f32 v[12:13], v[28:29], v[12:13], v[40:41]
	v_cvt_pk_bf16_f32 v21, v10, v11
	v_pk_fma_f32 v[10:11], v[30:31], v[14:15], v[42:43]
	v_pk_fma_f32 v[12:13], v[36:37], v[220:221], v[12:13]
	v_pk_fma_f32 v[10:11], v[38:39], v[218:219], v[10:11]
	v_pk_fma_f32 v[12:13], v[216:217], v[32:33], v[12:13]
	v_pk_fma_f32 v[10:11], v[214:215], v[34:35], v[10:11]
	v_pk_fma_f32 v[12:13], v[210:211], v[24:25], v[12:13]
	v_pk_fma_f32 v[10:11], v[212:213], v[26:27], v[10:11]
	v_cvt_pk_bf16_f32 v18, v12, v13
	v_pk_fma_f32 v[12:13], v[28:29], v[220:221], v[40:41]
	v_cvt_pk_bf16_f32 v19, v10, v11
	v_pk_fma_f32 v[10:11], v[30:31], v[218:219], v[42:43]
	v_pk_mul_f32 v[236:237], v[8:9], v[158:159]
	v_mov_b32_e32 v238, v7
	v_pk_fma_f32 v[10:11], v[38:39], v[214:215], v[10:11]
	v_pk_fma_f32 v[12:13], v[36:37], v[216:217], v[12:13]
	v_pk_mul_f32 v[236:237], v[238:239], v[236:237] op_sel_hi:[0,1]
	v_pk_mul_f32 v[234:235], v[238:239], v[234:235] op_sel_hi:[0,1]
	v_pk_fma_f32 v[10:11], v[212:213], v[34:35], v[10:11]
	v_pk_fma_f32 v[12:13], v[210:211], v[32:33], v[12:13]
	v_pk_fma_f32 v[10:11], v[234:235], v[26:27], v[10:11]
	v_pk_fma_f32 v[12:13], v[236:237], v[24:25], v[12:13]
	v_pk_mul_f32 v[8:9], v[8:9], v[162:163]
	v_cvt_pk_bf16_f32 v16, v12, v13
	v_cvt_pk_bf16_f32 v17, v10, v11
	v_pk_fma_f32 v[10:11], v[30:31], v[214:215], v[42:43]
	v_pk_fma_f32 v[12:13], v[28:29], v[216:217], v[40:41]
	v_pk_fma_f32 v[10:11], v[38:39], v[212:213], v[10:11]
	v_pk_fma_f32 v[12:13], v[36:37], v[210:211], v[12:13]
	v_pk_mul_f32 v[8:9], v[0:1], v[8:9] op_sel_hi:[0,1]
	v_pk_fma_f32 v[12:13], v[236:237], v[32:33], v[12:13]
	v_pk_fma_f32 v[10:11], v[234:235], v[34:35], v[10:11]
	v_pk_fma_f32 v[12:13], v[8:9], v[24:25], v[12:13]
	v_pk_fma_f32 v[10:11], v[202:203], v[26:27], v[10:11]
	v_cvt_pk_bf16_f32 v14, v12, v13
	v_pk_fma_f32 v[12:13], v[28:29], v[210:211], v[40:41]
	v_cvt_pk_bf16_f32 v15, v10, v11
	v_pk_fma_f32 v[10:11], v[30:31], v[212:213], v[42:43]
	v_pk_fma_f32 v[12:13], v[36:37], v[236:237], v[12:13]
	v_pk_fma_f32 v[10:11], v[38:39], v[234:235], v[10:11]
	v_pk_fma_f32 v[12:13], v[8:9], v[32:33], v[12:13]
	v_pk_fma_f32 v[10:11], v[202:203], v[34:35], v[10:11]
	v_pk_fma_f32 v[12:13], v[48:49], v[24:25], v[12:13]
	v_pk_fma_f32 v[10:11], v[206:207], v[26:27], v[10:11]
	v_cvt_pk_bf16_f32 v12, v12, v13
	v_pk_fma_f32 v[210:211], v[30:31], v[234:235], v[42:43]
	v_cvt_pk_bf16_f32 v13, v10, v11
	v_pk_fma_f32 v[10:11], v[28:29], v[236:237], v[40:41]
	v_pk_fma_f32 v[210:211], v[38:39], v[202:203], v[210:211]
	v_pk_fma_f32 v[10:11], v[36:37], v[8:9], v[10:11]
	v_pk_fma_f32 v[8:9], v[28:29], v[8:9], v[40:41]
	v_pk_fma_f32 v[28:29], v[30:31], v[202:203], v[42:43]
	v_pk_fma_f32 v[8:9], v[36:37], v[48:49], v[8:9]
	v_pk_fma_f32 v[28:29], v[38:39], v[206:207], v[28:29]
	v_pk_fma_f32 v[10:11], v[48:49], v[32:33], v[10:11]
	v_pk_fma_f32 v[210:211], v[206:207], v[34:35], v[210:211]
	v_pk_fma_f32 v[8:9], v[208:209], v[32:33], v[8:9]
	v_pk_fma_f32 v[28:29], v[46:47], v[34:35], v[28:29]
	v_pk_fma_f32 v[210:211], v[46:47], v[26:27], v[210:211]
	v_pk_fma_f32 v[10:11], v[208:209], v[24:25], v[10:11]
	v_pk_fma_f32 v[26:27], v[44:45], v[26:27], v[28:29]
	v_pk_fma_f32 v[2:3], v[2:3], v[24:25], v[8:9]
	v_cvt_pk_bf16_f32 v10, v10, v11
	v_cvt_pk_bf16_f32 v11, v210, v211
	s_nop 0
	v_cvt_pk_bf16_f32 v8, v2, v3
	v_cvt_pk_bf16_f32 v9, v26, v27
	v_or_b32_e32 v214, 4, v152
	v_ashrrev_i32_e32 v215, 31, v214
	v_mov_b32_e32 v24, 0
	v_mov_b32_e32 v25, 0
	v_mov_b32_e32 v212, 0
	v_mov_b32_e32 v213, 0
	v_mov_b32_e32 v208, 0
	v_mov_b32_e32 v209, 0
	v_mov_b32_e32 v210, 0
	v_mov_b32_e32 v211, 0
	v_mov_b32_e32 v202, 0
	v_mov_b32_e32 v203, 0
	v_mov_b32_e32 v206, 0
	v_mov_b32_e32 v207, 0
	v_mov_b32_e32 v168, v4
	v_mov_b32_e32 v169, v4
	v_mov_b32_e32 v166, v5
	v_mov_b32_e32 v167, v5
	v_mov_b32_e32 v164, v6
	v_mov_b32_e32 v165, v6
	v_mov_b32_e32 v158, v7
	v_mov_b32_e32 v159, v7
	v_mov_b32_e32 v160, v7
	v_mov_b32_e32 v161, v7
	v_mov_b32_e32 v162, v0
	v_mov_b32_e32 v163, v0
	v_cmp_gt_i32_e32 vcc, 15, v223
	s_mov_b64 s[8:9], -1
	s_waitcnt vmcnt(0)
	v_pk_mul_f32 v[30:31], v[240:241], v[194:195]
	v_pk_mul_f32 v[2:3], v[242:243], v[192:193]
	v_pk_mul_f32 v[32:33], v[242:243], v[200:201]
	v_pk_mul_f32 v[34:35], v[240:241], v[198:199]
	v_pk_mul_f32 v[192:193], v[106:107], v[30:31]
	v_lshlrev_b64 v[30:31], 2, v[214:215]
	v_pk_mul_f32 v[26:27], v[240:241], v[190:191]
	v_pk_mul_f32 v[28:29], v[242:243], v[196:197]
	v_pk_mul_f32 v[198:199], v[104:105], v[2:3]
	v_pk_mul_f32 v[190:191], v[122:123], v[32:33]
	v_pk_mul_f32 v[2:3], v[118:119], v[34:35]
	v_lshl_add_u64 v[32:33], s[40:41], 0, v[30:31]
	v_lshl_add_u64 v[34:35], s[42:43], 0, v[30:31]
	v_lshl_add_u64 v[30:31], s[44:45], 0, v[30:31]
	v_pk_mul_f32 v[194:195], v[102:103], v[26:27]
	v_pk_mul_f32 v[196:197], v[110:111], v[28:29]
	global_load_dwordx4 v[26:29], v[154:155], off offset:16
	global_load_dwordx4 v[38:41], v[32:33], off
	s_nop 0
	global_load_dwordx4 v[34:37], v[34:35], off
	s_nop 0
	global_load_dwordx4 v[30:33], v[30:31], off
	s_nop 0
	global_load_dwordx4 v[42:45], v[156:157], off offset:16
	v_mov_b32_dpp v24, v194 row_shr:1 row_mask:0xf bank_mask:0xf
	v_mov_b32_dpp v25, v195 row_shr:1 row_mask:0xf bank_mask:0xf
	v_mov_b32_dpp v212, v198 row_shr:1 row_mask:0xf bank_mask:0xf
	v_mov_b32_dpp v213, v199 row_shr:1 row_mask:0xf bank_mask:0xf
	v_mov_b32_dpp v208, v192 row_shr:1 row_mask:0xf bank_mask:0xf
	v_mov_b32_dpp v209, v193 row_shr:1 row_mask:0xf bank_mask:0xf
	v_mov_b32_dpp v210, v196 row_shr:1 row_mask:0xf bank_mask:0xf
	v_mov_b32_dpp v211, v197 row_shr:1 row_mask:0xf bank_mask:0xf
	v_mov_b32_dpp v202, v2 row_shr:1 row_mask:0xf bank_mask:0xf
	v_mov_b32_dpp v203, v3 row_shr:1 row_mask:0xf bank_mask:0xf
	v_mov_b32_dpp v206, v190 row_shr:1 row_mask:0xf bank_mask:0xf
	v_mov_b32_dpp v207, v191 row_shr:1 row_mask:0xf bank_mask:0xf
	s_and_saveexec_b64 s[54:55], vcc
	v_cmp_eq_u32_e32 vcc, 0, v223
	s_orn2_b64 s[8:9], vcc, exec
	s_or_b64 exec, exec, s[54:55]
	v_pk_mul_f32 v[188:189], v[242:243], v[188:189]
	v_pk_mul_f32 v[182:183], v[240:241], v[182:183]
	v_mov_b32_e32 v200, v4
	v_mov_b32_e32 v201, v4
	v_pk_mul_f32 v[188:189], v[200:201], v[188:189]
	v_pk_mul_f32 v[200:201], v[168:169], v[182:183]
	v_pk_mul_f32 v[182:183], v[242:243], v[186:187]
	v_pk_mul_f32 v[180:181], v[240:241], v[180:181]
	v_mov_b32_e32 v186, v5
	v_mov_b32_e32 v187, v5
	v_pk_mul_f32 v[182:183], v[186:187], v[182:183]
	v_pk_mul_f32 v[186:187], v[166:167], v[180:181]
	v_pk_mul_f32 v[180:181], v[242:243], v[184:185]
	v_pk_mul_f32 v[184:185], v[240:241], v[178:179]
	v_mov_b32_e32 v7, v6
	v_pk_mul_f32 v[178:179], v[6:7], v[180:181]
	v_pk_mul_f32 v[180:181], v[164:165], v[184:185]
	s_and_saveexec_b64 s[54:55], s[8:9]
	s_cbranch_execz .LBB0_383
	v_lshlrev_b64 v[216:217], 11, v[148:149]
	v_lshl_add_u64 v[216:217], s[30:31], 0, v[216:217]
	v_cndmask_b32_e64 v184, v194, v200, s[4:5]
	v_cndmask_b32_e64 v185, v195, v201, s[4:5]
	v_lshl_add_u64 v[216:217], v[216:217], 0, v[120:121]
	v_cndmask_b32_e64 v7, v198, v188, s[4:5]
	v_cndmask_b32_e64 v153, v199, v189, s[4:5]
	v_cvt_pk_bf16_f32 v184, v184, v185
	v_cvt_pk_bf16_f32 v185, v7, v153
	global_store_dwordx2 v[216:217], v[184:185], off offset:8
	v_lshlrev_b64 v[216:217], 11, v[146:147]
	v_lshl_add_u64 v[216:217], s[30:31], 0, v[216:217]
	v_cndmask_b32_e64 v184, v192, v186, s[4:5]
	v_cndmask_b32_e64 v185, v193, v187, s[4:5]
	v_lshl_add_u64 v[216:217], v[216:217], 0, v[120:121]
	v_cndmask_b32_e64 v7, v196, v182, s[4:5]
	v_cndmask_b32_e64 v153, v197, v183, s[4:5]
	v_cvt_pk_bf16_f32 v184, v184, v185
	v_cvt_pk_bf16_f32 v185, v7, v153
	global_store_dwordx2 v[216:217], v[184:185], off offset:8
	v_lshlrev_b64 v[216:217], 11, v[124:125]
	v_lshl_add_u64 v[216:217], s[30:31], 0, v[216:217]
	v_cndmask_b32_e64 v184, v2, v180, s[4:5]
	v_cndmask_b32_e64 v185, v3, v181, s[4:5]
	v_lshl_add_u64 v[216:217], v[216:217], 0, v[120:121]
	v_cndmask_b32_e64 v7, v190, v178, s[4:5]
	v_cndmask_b32_e64 v153, v191, v179, s[4:5]
	v_cvt_pk_bf16_f32 v184, v184, v185
	v_cvt_pk_bf16_f32 v185, v7, v153
	global_store_dwordx2 v[216:217], v[184:185], off offset:8
.LBB0_383:
	s_or_b64 exec, exec, s[54:55]
	v_pk_mul_f32 v[172:173], v[242:243], v[172:173]
	s_waitcnt vmcnt(0)
	v_pk_fma_f32 v[24:25], v[26:27], v[24:25], v[42:43]
	v_pk_mul_f32 v[184:185], v[160:161], v[172:173]
	v_pk_fma_f32 v[172:173], v[28:29], v[212:213], v[44:45]
	v_pk_fma_f32 v[24:25], v[38:39], v[208:209], v[24:25]
	v_pk_fma_f32 v[172:173], v[40:41], v[210:211], v[172:173]
	v_pk_fma_f32 v[24:25], v[34:35], v[202:203], v[24:25]
	v_pk_fma_f32 v[172:173], v[36:37], v[206:207], v[172:173]
	v_lshl_add_u32 v7, v214, 1, -8
	v_pk_fma_f32 v[172:173], v[188:189], v[32:33], v[172:173]
	v_pk_fma_f32 v[24:25], v[200:201], v[30:31], v[24:25]
	v_lshlrev_b32_e32 v153, 11, v204
	v_cvt_pk_bf16_f32 v24, v24, v25
	v_cvt_pk_bf16_f32 v25, v172, v173
	v_add_u32_e32 v172, v7, v153
	global_store_dwordx4 v172, v[22:25], s[28:29]
	v_pk_mul_f32 v[170:171], v[240:241], v[170:171]
	v_pk_mul_f32 v[46:47], v[240:241], v[174:175]
	v_pk_fma_f32 v[22:23], v[28:29], v[210:211], v[44:45]
	v_pk_fma_f32 v[24:25], v[26:27], v[208:209], v[42:43]
	v_pk_fma_f32 v[22:23], v[40:41], v[206:207], v[22:23]
	v_pk_fma_f32 v[24:25], v[38:39], v[202:203], v[24:25]
	v_pk_fma_f32 v[22:23], v[188:189], v[36:37], v[22:23]
	v_pk_fma_f32 v[24:25], v[200:201], v[34:35], v[24:25]
	v_pk_fma_f32 v[172:173], v[182:183], v[32:33], v[22:23]
	v_pk_fma_f32 v[22:23], v[186:187], v[30:31], v[24:25]
	v_pk_mul_f32 v[170:171], v[158:159], v[170:171]
	v_cvt_pk_bf16_f32 v22, v22, v23
	v_cvt_pk_bf16_f32 v23, v172, v173
	v_or_b32_e32 v172, 0x800, v153
	v_add_u32_e32 v24, v7, v172
	global_store_dwordx4 v24, v[20:23], s[28:29]
	v_or_b32_e32 v173, 0x1000, v153
	v_or_b32_e32 v174, 0x1800, v153
	v_pk_fma_f32 v[20:21], v[28:29], v[206:207], v[44:45]
	v_pk_fma_f32 v[22:23], v[26:27], v[202:203], v[42:43]
	v_pk_fma_f32 v[20:21], v[40:41], v[188:189], v[20:21]
	v_pk_fma_f32 v[22:23], v[38:39], v[200:201], v[22:23]
	v_pk_fma_f32 v[20:21], v[182:183], v[36:37], v[20:21]
	v_pk_fma_f32 v[22:23], v[186:187], v[34:35], v[22:23]
	v_pk_fma_f32 v[24:25], v[178:179], v[32:33], v[20:21]
	v_pk_fma_f32 v[20:21], v[180:181], v[30:31], v[22:23]
	v_add_u32_e32 v22, v7, v173
	v_cvt_pk_bf16_f32 v20, v20, v21
	v_cvt_pk_bf16_f32 v21, v24, v25
	global_store_dwordx4 v22, v[18:21], s[28:29]
	v_pk_mul_f32 v[48:49], v[242:243], v[176:177]
	v_pk_mul_f32 v[46:47], v[0:1], v[46:47]
	v_pk_fma_f32 v[18:19], v[28:29], v[188:189], v[44:45]
	v_pk_fma_f32 v[20:21], v[26:27], v[200:201], v[42:43]
	v_pk_fma_f32 v[18:19], v[40:41], v[182:183], v[18:19]
	v_pk_fma_f32 v[20:21], v[38:39], v[186:187], v[20:21]
	v_pk_fma_f32 v[18:19], v[178:179], v[36:37], v[18:19]
	v_pk_fma_f32 v[20:21], v[180:181], v[34:35], v[20:21]
	v_pk_fma_f32 v[22:23], v[184:185], v[32:33], v[18:19]
	v_pk_fma_f32 v[18:19], v[170:171], v[30:31], v[20:21]
	v_add_u32_e32 v20, v7, v174
	v_cvt_pk_bf16_f32 v18, v18, v19
	v_cvt_pk_bf16_f32 v19, v22, v23
	global_store_dwordx4 v20, v[16:19], s[28:29]
	v_pk_mul_f32 v[48:49], v[162:163], v[48:49]
	v_or_b32_e32 v175, 0x2000, v153
	v_pk_fma_f32 v[16:17], v[28:29], v[182:183], v[44:45]
	v_pk_fma_f32 v[18:19], v[26:27], v[186:187], v[42:43]
	v_pk_fma_f32 v[16:17], v[40:41], v[178:179], v[16:17]
	v_pk_fma_f32 v[18:19], v[38:39], v[180:181], v[18:19]
	v_pk_fma_f32 v[16:17], v[184:185], v[36:37], v[16:17]
	v_pk_fma_f32 v[18:19], v[170:171], v[34:35], v[18:19]
	v_pk_fma_f32 v[20:21], v[48:49], v[32:33], v[16:17]
	v_pk_fma_f32 v[16:17], v[46:47], v[30:31], v[18:19]
	v_add_u32_e32 v18, v7, v175
	v_cvt_pk_bf16_f32 v16, v16, v17
	v_cvt_pk_bf16_f32 v17, v20, v21
	global_store_dwordx4 v18, v[14:17], s[28:29]
	v_or_b32_e32 v176, 0x2800, v153
	v_or_b32_e32 v177, 0x3000, v153
	v_pk_fma_f32 v[14:15], v[28:29], v[178:179], v[44:45]
	v_pk_fma_f32 v[16:17], v[26:27], v[180:181], v[42:43]
	v_pk_fma_f32 v[14:15], v[40:41], v[184:185], v[14:15]
	v_pk_fma_f32 v[16:17], v[38:39], v[170:171], v[16:17]
	v_pk_fma_f32 v[14:15], v[48:49], v[36:37], v[14:15]
	v_pk_fma_f32 v[16:17], v[46:47], v[34:35], v[16:17]
	v_pk_fma_f32 v[18:19], v[198:199], v[32:33], v[14:15]
	v_pk_fma_f32 v[14:15], v[194:195], v[30:31], v[16:17]
	v_add_u32_e32 v16, v7, v176
	v_cvt_pk_bf16_f32 v14, v14, v15
	v_cvt_pk_bf16_f32 v15, v18, v19
	global_store_dwordx4 v16, v[12:15], s[28:29]
	v_or_b32_e32 v178, 0x3800, v153
	s_nop 0
	v_pk_fma_f32 v[12:13], v[28:29], v[184:185], v[44:45]
	v_pk_fma_f32 v[14:15], v[26:27], v[170:171], v[42:43]
	v_pk_fma_f32 v[12:13], v[40:41], v[48:49], v[12:13]
	v_pk_fma_f32 v[14:15], v[38:39], v[46:47], v[14:15]
	v_pk_fma_f32 v[12:13], v[198:199], v[36:37], v[12:13]
	v_pk_fma_f32 v[14:15], v[194:195], v[34:35], v[14:15]
	v_pk_fma_f32 v[16:17], v[196:197], v[32:33], v[12:13]
	v_pk_fma_f32 v[12:13], v[192:193], v[30:31], v[14:15]
	v_add_u32_e32 v14, v7, v177
	v_cvt_pk_bf16_f32 v12, v12, v13
	v_cvt_pk_bf16_f32 v13, v16, v17
	global_store_dwordx4 v14, v[10:13], s[28:29]
	s_nop 1
	v_pk_fma_f32 v[12:13], v[26:27], v[46:47], v[42:43]
	v_pk_fma_f32 v[10:11], v[28:29], v[48:49], v[44:45]
	v_pk_fma_f32 v[12:13], v[38:39], v[194:195], v[12:13]
	v_pk_fma_f32 v[10:11], v[40:41], v[198:199], v[10:11]
	v_pk_fma_f32 v[12:13], v[192:193], v[34:35], v[12:13]
	v_pk_fma_f32 v[10:11], v[196:197], v[36:37], v[10:11]
	v_pk_fma_f32 v[2:3], v[2:3], v[30:31], v[12:13]
	v_pk_fma_f32 v[14:15], v[190:191], v[32:33], v[10:11]
	v_cvt_pk_bf16_f32 v10, v2, v3
	v_add_u32_e32 v2, v7, v178
	v_cvt_pk_bf16_f32 v11, v14, v15
	global_store_dwordx4 v2, v[8:11], s[28:29]
	v_mov_b32_e32 v20, 0
	v_mov_b32_e32 v21, 0
	v_mov_b32_e32 v170, 0
	v_mov_b32_e32 v171, 0
	v_mov_b32_e32 v16, 0
	v_mov_b32_e32 v17, 0
	v_mov_b32_e32 v18, 0
	v_mov_b32_e32 v19, 0
	v_mov_b32_e32 v12, 0
	v_mov_b32_e32 v13, 0
	v_mov_b32_e32 v14, 0
	v_mov_b32_e32 v15, 0
	v_cmp_gt_i32_e32 vcc, 15, v223
	s_mov_b64 s[8:9], -1
	s_waitcnt vmcnt(0)
	v_pk_mul_f32 v[26:27], v[244:245], v[114:115]
	s_nop 0
	v_pk_mul_f32 v[44:45], v[106:107], v[26:27]
	v_or_b32_e32 v26, 0x80, v152
	v_ashrrev_i32_e32 v27, 31, v26
	v_pk_mul_f32 v[2:3], v[246:247], v[112:113]
	v_pk_mul_f32 v[28:29], v[246:247], v[144:145]
	v_pk_mul_f32 v[30:31], v[244:245], v[126:127]
	v_lshlrev_b64 v[26:27], 2, v[26:27]
	v_pk_mul_f32 v[22:23], v[244:245], v[108:109]
	v_pk_mul_f32 v[24:25], v[246:247], v[116:117]
	v_pk_mul_f32 v[108:109], v[104:105], v[2:3]
	v_pk_mul_f32 v[42:43], v[122:123], v[28:29]
	v_pk_mul_f32 v[2:3], v[118:119], v[30:31]
	v_lshl_add_u64 v[28:29], s[40:41], 0, v[26:27]
	v_lshl_add_u64 v[30:31], s[42:43], 0, v[26:27]
	v_lshl_add_u64 v[26:27], s[44:45], 0, v[26:27]
	v_pk_mul_f32 v[46:47], v[102:103], v[22:23]
	v_pk_mul_f32 v[48:49], v[110:111], v[24:25]
	global_load_dwordx4 v[22:25], v[154:155], off offset:512
	global_load_dwordx4 v[34:37], v[28:29], off
	s_nop 0
	global_load_dwordx4 v[30:33], v[30:31], off
	s_nop 0
	global_load_dwordx4 v[26:29], v[26:27], off
	s_nop 0
	global_load_dwordx4 v[38:41], v[156:157], off offset:512
	v_mov_b32_dpp v20, v46 row_shr:1 row_mask:0xf bank_mask:0xf
	v_mov_b32_dpp v21, v47 row_shr:1 row_mask:0xf bank_mask:0xf
	v_mov_b32_dpp v170, v108 row_shr:1 row_mask:0xf bank_mask:0xf
	v_mov_b32_dpp v171, v109 row_shr:1 row_mask:0xf bank_mask:0xf
	v_mov_b32_dpp v16, v44 row_shr:1 row_mask:0xf bank_mask:0xf
	v_mov_b32_dpp v17, v45 row_shr:1 row_mask:0xf bank_mask:0xf
	v_mov_b32_dpp v18, v48 row_shr:1 row_mask:0xf bank_mask:0xf
	v_mov_b32_dpp v19, v49 row_shr:1 row_mask:0xf bank_mask:0xf
	v_mov_b32_dpp v12, v2 row_shr:1 row_mask:0xf bank_mask:0xf
	v_mov_b32_dpp v13, v3 row_shr:1 row_mask:0xf bank_mask:0xf
	v_mov_b32_dpp v14, v42 row_shr:1 row_mask:0xf bank_mask:0xf
	v_mov_b32_dpp v15, v43 row_shr:1 row_mask:0xf bank_mask:0xf
	s_and_saveexec_b64 s[54:55], vcc
	v_cmp_eq_u32_e32 vcc, 0, v223
	s_orn2_b64 s[8:9], vcc, exec
	s_or_b64 exec, exec, s[54:55]
	v_pk_mul_f32 v[100:101], v[246:247], v[100:101]
	v_pk_mul_f32 v[94:95], v[244:245], v[94:95]
	v_mov_b32_e32 v112, v4
	v_mov_b32_e32 v113, v4
	v_pk_mul_f32 v[100:101], v[112:113], v[100:101]
	v_pk_mul_f32 v[112:113], v[168:169], v[94:95]
	v_pk_mul_f32 v[94:95], v[246:247], v[98:99]
	v_pk_mul_f32 v[92:93], v[244:245], v[92:93]
	v_mov_b32_e32 v98, v5
	v_mov_b32_e32 v99, v5
	v_pk_mul_f32 v[94:95], v[98:99], v[94:95]
	v_pk_mul_f32 v[98:99], v[166:167], v[92:93]
	v_pk_mul_f32 v[92:93], v[246:247], v[96:97]
	v_pk_mul_f32 v[96:97], v[244:245], v[90:91]
	v_mov_b32_e32 v7, v6
	v_pk_mul_f32 v[90:91], v[6:7], v[92:93]
	v_pk_mul_f32 v[92:93], v[164:165], v[96:97]
	s_and_saveexec_b64 s[54:55], s[8:9]
	s_cbranch_execz .LBB0_387
	v_cndmask_b32_e64 v96, v46, v112, s[4:5]
	v_cndmask_b32_e64 v114, v47, v113, s[4:5]
	v_cvt_pk_bf16_f32 v96, v96, v114
	v_lshlrev_b64 v[114:115], 11, v[148:149]
	v_lshl_add_u64 v[114:115], s[30:31], 0, v[114:115]
	v_cndmask_b32_e64 v97, v109, v101, s[4:5]
	v_lshl_add_u64 v[114:115], v[114:115], 0, v[120:121]
	v_cndmask_b32_e64 v7, v108, v100, s[4:5]
	v_cvt_pk_bf16_f32 v97, v7, v97
	global_store_dwordx2 v[114:115], v[96:97], off offset:256
	v_cndmask_b32_e64 v96, v44, v98, s[4:5]
	v_cndmask_b32_e64 v114, v45, v99, s[4:5]
	v_cvt_pk_bf16_f32 v96, v96, v114
	v_lshlrev_b64 v[114:115], 11, v[146:147]
	v_lshl_add_u64 v[114:115], s[30:31], 0, v[114:115]
	v_cndmask_b32_e64 v97, v49, v95, s[4:5]
	v_lshl_add_u64 v[114:115], v[114:115], 0, v[120:121]
	v_cndmask_b32_e64 v7, v48, v94, s[4:5]
	v_cvt_pk_bf16_f32 v97, v7, v97
	global_store_dwordx2 v[114:115], v[96:97], off offset:256
	v_cndmask_b32_e64 v96, v2, v92, s[4:5]
	v_cndmask_b32_e64 v114, v3, v93, s[4:5]
	v_cvt_pk_bf16_f32 v96, v96, v114
	v_lshlrev_b64 v[114:115], 11, v[124:125]
	v_lshl_add_u64 v[114:115], s[30:31], 0, v[114:115]
	v_cndmask_b32_e64 v97, v43, v91, s[4:5]
	v_lshl_add_u64 v[114:115], v[114:115], 0, v[120:121]
	v_cndmask_b32_e64 v7, v42, v90, s[4:5]
	v_cvt_pk_bf16_f32 v97, v7, v97
	global_store_dwordx2 v[114:115], v[96:97], off offset:256
.LBB0_387:
	s_or_b64 exec, exec, s[54:55]
	v_pk_mul_f32 v[84:85], v[246:247], v[84:85]
	v_pk_mul_f32 v[82:83], v[244:245], v[82:83]
	v_pk_mul_f32 v[10:11], v[246:247], v[88:89]
	v_pk_mul_f32 v[8:9], v[244:245], v[86:87]
	v_pk_mul_f32 v[86:87], v[162:163], v[10:11]
	v_pk_mul_f32 v[88:89], v[0:1], v[8:9]
	s_waitcnt vmcnt(0)
	v_pk_fma_f32 v[8:9], v[24:25], v[170:171], v[40:41]
	v_pk_fma_f32 v[10:11], v[22:23], v[20:21], v[38:39]
	v_pk_fma_f32 v[8:9], v[36:37], v[18:19], v[8:9]
	v_pk_fma_f32 v[10:11], v[34:35], v[16:17], v[10:11]
	v_pk_fma_f32 v[8:9], v[32:33], v[14:15], v[8:9]
	v_pk_fma_f32 v[10:11], v[30:31], v[12:13], v[10:11]
	v_pk_fma_f32 v[8:9], v[100:101], v[28:29], v[8:9]
	v_pk_fma_f32 v[10:11], v[112:113], v[26:27], v[10:11]
	v_pk_mul_f32 v[84:85], v[160:161], v[84:85]
	v_cvt_pk_bf16_f32 v20, v10, v11
	v_cvt_pk_bf16_f32 v21, v8, v9
	v_pk_fma_f32 v[8:9], v[24:25], v[18:19], v[40:41]
	v_pk_fma_f32 v[10:11], v[22:23], v[16:17], v[38:39]
	v_pk_fma_f32 v[8:9], v[36:37], v[14:15], v[8:9]
	v_pk_fma_f32 v[10:11], v[34:35], v[12:13], v[10:11]
	v_pk_fma_f32 v[8:9], v[100:101], v[32:33], v[8:9]
	v_pk_fma_f32 v[10:11], v[112:113], v[30:31], v[10:11]
	v_pk_fma_f32 v[8:9], v[94:95], v[28:29], v[8:9]
	v_pk_fma_f32 v[10:11], v[98:99], v[26:27], v[10:11]
	v_pk_mul_f32 v[82:83], v[158:159], v[82:83]
	v_cvt_pk_bf16_f32 v18, v10, v11
	v_cvt_pk_bf16_f32 v19, v8, v9
	v_pk_fma_f32 v[8:9], v[24:25], v[14:15], v[40:41]
	v_pk_fma_f32 v[10:11], v[22:23], v[12:13], v[38:39]
	v_pk_fma_f32 v[8:9], v[36:37], v[100:101], v[8:9]
	v_pk_fma_f32 v[10:11], v[34:35], v[112:113], v[10:11]
	v_pk_fma_f32 v[8:9], v[94:95], v[32:33], v[8:9]
	v_pk_fma_f32 v[10:11], v[98:99], v[30:31], v[10:11]
	v_pk_fma_f32 v[8:9], v[90:91], v[28:29], v[8:9]
	v_pk_fma_f32 v[10:11], v[92:93], v[26:27], v[10:11]
	s_nop 0
	v_cvt_pk_bf16_f32 v16, v10, v11
	v_cvt_pk_bf16_f32 v17, v8, v9
	v_pk_fma_f32 v[8:9], v[24:25], v[100:101], v[40:41]
	v_pk_fma_f32 v[10:11], v[22:23], v[112:113], v[38:39]
	v_pk_fma_f32 v[8:9], v[36:37], v[94:95], v[8:9]
	v_pk_fma_f32 v[10:11], v[34:35], v[98:99], v[10:11]
	v_pk_fma_f32 v[8:9], v[90:91], v[32:33], v[8:9]
	v_pk_fma_f32 v[10:11], v[92:93], v[30:31], v[10:11]
	v_pk_fma_f32 v[8:9], v[84:85], v[28:29], v[8:9]
	v_pk_fma_f32 v[10:11], v[82:83], v[26:27], v[10:11]
	s_nop 0
	v_cvt_pk_bf16_f32 v14, v10, v11
	v_cvt_pk_bf16_f32 v15, v8, v9
	v_pk_fma_f32 v[8:9], v[24:25], v[94:95], v[40:41]
	v_pk_fma_f32 v[10:11], v[22:23], v[98:99], v[38:39]
	v_pk_fma_f32 v[8:9], v[36:37], v[90:91], v[8:9]
	v_pk_fma_f32 v[10:11], v[34:35], v[92:93], v[10:11]
	v_pk_fma_f32 v[8:9], v[84:85], v[32:33], v[8:9]
	v_pk_fma_f32 v[10:11], v[82:83], v[30:31], v[10:11]
	v_pk_fma_f32 v[8:9], v[86:87], v[28:29], v[8:9]
	v_pk_fma_f32 v[10:11], v[88:89], v[26:27], v[10:11]
	s_nop 0
	v_cvt_pk_bf16_f32 v12, v10, v11
	v_cvt_pk_bf16_f32 v13, v8, v9
	v_pk_fma_f32 v[8:9], v[24:25], v[90:91], v[40:41]
	v_pk_fma_f32 v[10:11], v[22:23], v[92:93], v[38:39]
	v_pk_fma_f32 v[8:9], v[36:37], v[84:85], v[8:9]
	v_pk_fma_f32 v[10:11], v[34:35], v[82:83], v[10:11]
	v_pk_fma_f32 v[8:9], v[86:87], v[32:33], v[8:9]
	v_pk_fma_f32 v[10:11], v[88:89], v[30:31], v[10:11]
	v_pk_fma_f32 v[8:9], v[108:109], v[28:29], v[8:9]
	v_pk_fma_f32 v[10:11], v[46:47], v[26:27], v[10:11]
	v_pk_fma_f32 v[82:83], v[22:23], v[82:83], v[38:39]
	v_cvt_pk_bf16_f32 v10, v10, v11
	v_cvt_pk_bf16_f32 v11, v8, v9
	v_pk_fma_f32 v[8:9], v[24:25], v[84:85], v[40:41]
	v_pk_fma_f32 v[24:25], v[24:25], v[86:87], v[40:41]
	v_pk_fma_f32 v[22:23], v[22:23], v[88:89], v[38:39]
	v_pk_fma_f32 v[8:9], v[36:37], v[86:87], v[8:9]
	v_pk_fma_f32 v[82:83], v[34:35], v[88:89], v[82:83]
	v_pk_fma_f32 v[24:25], v[36:37], v[108:109], v[24:25]
	v_pk_fma_f32 v[22:23], v[34:35], v[46:47], v[22:23]
	v_pk_fma_f32 v[8:9], v[108:109], v[32:33], v[8:9]
	v_pk_fma_f32 v[82:83], v[46:47], v[30:31], v[82:83]
	v_pk_fma_f32 v[24:25], v[48:49], v[32:33], v[24:25]
	v_pk_fma_f32 v[22:23], v[44:45], v[30:31], v[22:23]
	v_pk_fma_f32 v[84:85], v[48:49], v[28:29], v[8:9]
	v_pk_fma_f32 v[8:9], v[44:45], v[26:27], v[82:83]
	v_pk_fma_f32 v[24:25], v[42:43], v[28:29], v[24:25]
	v_pk_fma_f32 v[2:3], v[2:3], v[26:27], v[22:23]
	v_cvt_pk_bf16_f32 v8, v8, v9
	v_cvt_pk_bf16_f32 v9, v84, v85
	s_nop 0
	v_cvt_pk_bf16_f32 v2, v2, v3
	v_cvt_pk_bf16_f32 v3, v24, v25
	v_or_b32_e32 v92, 0x84, v152
	v_ashrrev_i32_e32 v93, 31, v92
	v_mov_b32_e32 v22, 0
	v_mov_b32_e32 v23, 0
	v_mov_b32_e32 v90, 0
	v_mov_b32_e32 v91, 0
	v_mov_b32_e32 v86, 0
	v_mov_b32_e32 v87, 0
	v_mov_b32_e32 v88, 0
	v_mov_b32_e32 v89, 0
	v_mov_b32_e32 v82, 0
	v_mov_b32_e32 v83, 0
	v_mov_b32_e32 v84, 0
	v_mov_b32_e32 v85, 0
	v_cmp_gt_i32_e32 vcc, 15, v223
	s_mov_b64 s[8:9], -1
	s_waitcnt vmcnt(0)
	v_pk_mul_f32 v[28:29], v[250:251], v[76:77]
	v_pk_mul_f32 v[30:31], v[248:249], v[74:75]
	v_pk_mul_f32 v[32:33], v[250:251], v[80:81]
	v_pk_mul_f32 v[76:77], v[110:111], v[28:29]
	v_lshlrev_b64 v[28:29], 2, v[92:93]
	v_pk_mul_f32 v[24:25], v[250:251], v[72:73]
	v_pk_mul_f32 v[26:27], v[248:249], v[70:71]
	v_pk_mul_f32 v[34:35], v[248:249], v[78:79]
	v_pk_mul_f32 v[72:73], v[106:107], v[30:31]
	v_pk_mul_f32 v[70:71], v[122:123], v[32:33]
	v_lshl_add_u64 v[30:31], s[40:41], 0, v[28:29]
	v_lshl_add_u64 v[32:33], s[42:43], 0, v[28:29]
	v_lshl_add_u64 v[28:29], s[44:45], 0, v[28:29]
	v_pk_mul_f32 v[78:79], v[104:105], v[24:25]
	v_pk_mul_f32 v[74:75], v[102:103], v[26:27]
	v_pk_mul_f32 v[48:49], v[118:119], v[34:35]
	global_load_dwordx4 v[24:27], v[154:155], off offset:528
	global_load_dwordx4 v[36:39], v[30:31], off
	s_nop 0
	global_load_dwordx4 v[32:35], v[32:33], off
	s_nop 0
	global_load_dwordx4 v[28:31], v[28:29], off
	s_nop 0
	global_load_dwordx4 v[40:43], v[156:157], off offset:528
	v_mov_b32_dpp v22, v74 row_shr:1 row_mask:0xf bank_mask:0xf
	v_mov_b32_dpp v23, v75 row_shr:1 row_mask:0xf bank_mask:0xf
	v_mov_b32_dpp v90, v78 row_shr:1 row_mask:0xf bank_mask:0xf
	v_mov_b32_dpp v91, v79 row_shr:1 row_mask:0xf bank_mask:0xf
	v_mov_b32_dpp v86, v72 row_shr:1 row_mask:0xf bank_mask:0xf
	v_mov_b32_dpp v87, v73 row_shr:1 row_mask:0xf bank_mask:0xf
	v_mov_b32_dpp v88, v76 row_shr:1 row_mask:0xf bank_mask:0xf
	v_mov_b32_dpp v89, v77 row_shr:1 row_mask:0xf bank_mask:0xf
	v_mov_b32_dpp v82, v48 row_shr:1 row_mask:0xf bank_mask:0xf
	v_mov_b32_dpp v83, v49 row_shr:1 row_mask:0xf bank_mask:0xf
	v_mov_b32_dpp v84, v70 row_shr:1 row_mask:0xf bank_mask:0xf
	v_mov_b32_dpp v85, v71 row_shr:1 row_mask:0xf bank_mask:0xf
	s_and_saveexec_b64 s[54:55], vcc
	v_cmp_eq_u32_e32 vcc, 0, v223
	s_orn2_b64 s[8:9], vcc, exec
	s_or_b64 exec, exec, s[54:55]
	v_pk_mul_f32 v[66:67], v[250:251], v[66:67]
	v_pk_mul_f32 v[60:61], v[248:249], v[60:61]
	v_mov_b32_e32 v80, v4
	v_mov_b32_e32 v81, v4
	v_pk_mul_f32 v[66:67], v[80:81], v[66:67]
	v_pk_mul_f32 v[80:81], v[168:169], v[60:61]
	v_pk_mul_f32 v[60:61], v[250:251], v[64:65]
	v_mov_b32_e32 v4, v5
	v_pk_mul_f32 v[64:65], v[248:249], v[56:57]
	v_pk_mul_f32 v[56:57], v[4:5], v[60:61]
	v_pk_mul_f32 v[4:5], v[250:251], v[62:63]
	v_pk_mul_f32 v[54:55], v[248:249], v[54:55]
	v_mov_b32_e32 v7, v6
	v_pk_mul_f32 v[60:61], v[166:167], v[64:65]
	v_pk_mul_f32 v[4:5], v[6:7], v[4:5]
	v_pk_mul_f32 v[6:7], v[164:165], v[54:55]
	s_and_saveexec_b64 s[54:55], s[8:9]
	s_cbranch_execz .LBB0_391
	v_cndmask_b32_e64 v55, v78, v66, s[4:5]
	v_cndmask_b32_e64 v62, v79, v67, s[4:5]
	v_cndmask_b32_e64 v54, v74, v80, s[4:5]
	v_cndmask_b32_e64 v63, v75, v81, s[4:5]
	v_cvt_pk_bf16_f32 v54, v54, v63
	v_cvt_pk_bf16_f32 v55, v55, v62
	v_lshlrev_b64 v[62:63], 11, v[148:149]
	v_lshl_add_u64 v[62:63], s[30:31], 0, v[62:63]
	v_lshl_add_u64 v[62:63], v[62:63], 0, v[120:121]
	global_store_dwordx2 v[62:63], v[54:55], off offset:264
	v_cndmask_b32_e64 v55, v76, v56, s[4:5]
	v_cndmask_b32_e64 v62, v77, v57, s[4:5]
	v_cndmask_b32_e64 v54, v72, v60, s[4:5]
	v_cndmask_b32_e64 v63, v73, v61, s[4:5]
	v_cvt_pk_bf16_f32 v54, v54, v63
	v_cvt_pk_bf16_f32 v55, v55, v62
	v_lshlrev_b64 v[62:63], 11, v[146:147]
	v_lshl_add_u64 v[62:63], s[30:31], 0, v[62:63]
	v_lshl_add_u64 v[62:63], v[62:63], 0, v[120:121]
	global_store_dwordx2 v[62:63], v[54:55], off offset:264
	v_cndmask_b32_e64 v55, v70, v4, s[4:5]
	v_cndmask_b32_e64 v62, v71, v5, s[4:5]
	v_cndmask_b32_e64 v54, v48, v6, s[4:5]
	v_cndmask_b32_e64 v63, v49, v7, s[4:5]
	v_cvt_pk_bf16_f32 v54, v54, v63
	v_cvt_pk_bf16_f32 v55, v55, v62
	v_lshlrev_b64 v[62:63], 11, v[124:125]
	v_lshl_add_u64 v[62:63], s[30:31], 0, v[62:63]
	v_lshl_add_u64 v[62:63], v[62:63], 0, v[120:121]
	global_store_dwordx2 v[62:63], v[54:55], off offset:264
.LBB0_391:
	s_or_b64 exec, exec, s[54:55]
	v_pk_mul_f32 v[58:59], v[248:249], v[58:59]
	v_pk_mul_f32 v[44:45], v[248:249], v[50:51]
	s_waitcnt vmcnt(0)
	v_pk_fma_f32 v[50:51], v[26:27], v[90:91], v[42:43]
	v_pk_fma_f32 v[22:23], v[24:25], v[22:23], v[40:41]
	v_pk_fma_f32 v[50:51], v[38:39], v[88:89], v[50:51]
	v_pk_fma_f32 v[22:23], v[36:37], v[86:87], v[22:23]
	v_pk_fma_f32 v[50:51], v[34:35], v[84:85], v[50:51]
	v_pk_fma_f32 v[22:23], v[32:33], v[82:83], v[22:23]
	v_pk_mul_f32 v[54:55], v[250:251], v[68:69]
	v_pk_mul_f32 v[46:47], v[250:251], v[52:53]
	v_lshl_add_u32 v52, v92, 1, -8
	v_pk_fma_f32 v[50:51], v[66:67], v[30:31], v[50:51]
	v_pk_fma_f32 v[22:23], v[80:81], v[28:29], v[22:23]
	v_pk_mul_f32 v[46:47], v[160:161], v[46:47]
	v_cvt_pk_bf16_f32 v22, v22, v23
	v_cvt_pk_bf16_f32 v23, v50, v51
	v_add_u32_e32 v50, v52, v153
	global_store_dwordx4 v50, v[20:23], s[28:29]
	v_pk_mul_f32 v[44:45], v[158:159], v[44:45]
	v_pk_mul_f32 v[54:55], v[162:163], v[54:55]
	v_pk_fma_f32 v[20:21], v[26:27], v[88:89], v[42:43]
	v_pk_fma_f32 v[22:23], v[24:25], v[86:87], v[40:41]
	v_pk_fma_f32 v[20:21], v[38:39], v[84:85], v[20:21]
	v_pk_fma_f32 v[22:23], v[36:37], v[82:83], v[22:23]
	v_pk_fma_f32 v[20:21], v[66:67], v[34:35], v[20:21]
	v_pk_fma_f32 v[22:23], v[80:81], v[32:33], v[22:23]
	v_pk_fma_f32 v[50:51], v[56:57], v[30:31], v[20:21]
	v_pk_fma_f32 v[20:21], v[60:61], v[28:29], v[22:23]
	v_add_u32_e32 v22, v52, v172
	v_cvt_pk_bf16_f32 v20, v20, v21
	v_cvt_pk_bf16_f32 v21, v50, v51
	global_store_dwordx4 v22, v[18:21], s[28:29]
	v_pk_mul_f32 v[0:1], v[0:1], v[58:59]
	s_andn2_b64 vcc, exec, s[14:15]
	v_pk_fma_f32 v[18:19], v[26:27], v[84:85], v[42:43]
	v_pk_fma_f32 v[20:21], v[24:25], v[82:83], v[40:41]
	v_pk_fma_f32 v[18:19], v[38:39], v[66:67], v[18:19]
	v_pk_fma_f32 v[20:21], v[36:37], v[80:81], v[20:21]
	v_pk_fma_f32 v[18:19], v[56:57], v[34:35], v[18:19]
	v_pk_fma_f32 v[20:21], v[60:61], v[32:33], v[20:21]
	v_pk_fma_f32 v[22:23], v[4:5], v[30:31], v[18:19]
	v_pk_fma_f32 v[18:19], v[6:7], v[28:29], v[20:21]
	v_add_u32_e32 v20, v52, v173
	v_cvt_pk_bf16_f32 v18, v18, v19
	v_cvt_pk_bf16_f32 v19, v22, v23
	global_store_dwordx4 v20, v[16:19], s[28:29]
	s_nop 1
	v_pk_fma_f32 v[16:17], v[26:27], v[66:67], v[42:43]
	v_pk_fma_f32 v[18:19], v[24:25], v[80:81], v[40:41]
	v_pk_fma_f32 v[16:17], v[38:39], v[56:57], v[16:17]
	v_pk_fma_f32 v[18:19], v[36:37], v[60:61], v[18:19]
	v_pk_fma_f32 v[16:17], v[4:5], v[34:35], v[16:17]
	v_pk_fma_f32 v[18:19], v[6:7], v[32:33], v[18:19]
	v_pk_fma_f32 v[20:21], v[46:47], v[30:31], v[16:17]
	v_pk_fma_f32 v[16:17], v[44:45], v[28:29], v[18:19]
	v_add_u32_e32 v18, v52, v174
	v_cvt_pk_bf16_f32 v16, v16, v17
	v_cvt_pk_bf16_f32 v17, v20, v21
	global_store_dwordx4 v18, v[14:17], s[28:29]
	s_nop 1
	v_pk_fma_f32 v[14:15], v[26:27], v[56:57], v[42:43]
	v_pk_fma_f32 v[16:17], v[24:25], v[60:61], v[40:41]
	v_pk_fma_f32 v[14:15], v[38:39], v[4:5], v[14:15]
	v_pk_fma_f32 v[4:5], v[26:27], v[4:5], v[42:43]
	v_pk_fma_f32 v[16:17], v[36:37], v[6:7], v[16:17]
	v_pk_fma_f32 v[6:7], v[24:25], v[6:7], v[40:41]
	v_pk_fma_f32 v[4:5], v[38:39], v[46:47], v[4:5]
	v_pk_fma_f32 v[14:15], v[46:47], v[34:35], v[14:15]
	v_pk_fma_f32 v[16:17], v[44:45], v[32:33], v[16:17]
	v_pk_fma_f32 v[6:7], v[36:37], v[44:45], v[6:7]
	v_pk_fma_f32 v[4:5], v[54:55], v[34:35], v[4:5]
	v_pk_fma_f32 v[18:19], v[54:55], v[30:31], v[14:15]
	v_pk_fma_f32 v[14:15], v[0:1], v[28:29], v[16:17]
	v_add_u32_e32 v16, v52, v175
	v_pk_fma_f32 v[6:7], v[0:1], v[32:33], v[6:7]
	v_pk_fma_f32 v[4:5], v[78:79], v[30:31], v[4:5]
	v_cvt_pk_bf16_f32 v14, v14, v15
	v_cvt_pk_bf16_f32 v15, v18, v19
	global_store_dwordx4 v16, v[12:15], s[28:29]
	v_pk_fma_f32 v[6:7], v[74:75], v[28:29], v[6:7]
	s_nop 0
	v_cvt_pk_bf16_f32 v12, v6, v7
	v_cvt_pk_bf16_f32 v13, v4, v5
	v_add_u32_e32 v4, v52, v176
	global_store_dwordx4 v4, v[10:13], s[28:29]
	v_pk_fma_f32 v[4:5], v[26:27], v[46:47], v[42:43]
	v_pk_fma_f32 v[6:7], v[24:25], v[44:45], v[40:41]
	v_pk_fma_f32 v[4:5], v[38:39], v[54:55], v[4:5]
	v_pk_fma_f32 v[6:7], v[36:37], v[0:1], v[6:7]
	v_pk_fma_f32 v[4:5], v[78:79], v[34:35], v[4:5]
	v_pk_fma_f32 v[6:7], v[74:75], v[32:33], v[6:7]
	v_pk_fma_f32 v[4:5], v[76:77], v[30:31], v[4:5]
	v_pk_fma_f32 v[6:7], v[72:73], v[28:29], v[6:7]
	v_pk_fma_f32 v[0:1], v[24:25], v[0:1], v[40:41]
	v_cvt_pk_bf16_f32 v10, v6, v7
	v_cvt_pk_bf16_f32 v11, v4, v5
	v_add_u32_e32 v4, v52, v177
	global_store_dwordx4 v4, v[8:11], s[28:29]
	v_pk_fma_f32 v[4:5], v[26:27], v[54:55], v[42:43]
	v_pk_fma_f32 v[0:1], v[36:37], v[74:75], v[0:1]
	v_pk_fma_f32 v[4:5], v[38:39], v[78:79], v[4:5]
	v_pk_fma_f32 v[0:1], v[72:73], v[32:33], v[0:1]
	v_pk_fma_f32 v[4:5], v[76:77], v[34:35], v[4:5]
	v_pk_fma_f32 v[0:1], v[48:49], v[28:29], v[0:1]
	v_pk_fma_f32 v[6:7], v[70:71], v[30:31], v[4:5]
	v_cvt_pk_bf16_f32 v4, v0, v1
	v_add_u32_e32 v0, v52, v178
	v_cvt_pk_bf16_f32 v5, v6, v7
	global_store_dwordx4 v0, v[2:5], s[28:29]
	s_cbranch_vccnz .LBB0_362
	s_barrier
	s_branch .LBB0_362
